# cache-policy tuning 2: nt (streaming) hint also on the 64 phase-4 SGU output stores, on top of v42
# baseline (speedup 1.0000x reference)
.LBB0_698:
	v_lshl_add_u32 v142, s4, 8, v138
	v_lshl_or_b32 v144, s5, 8, v140
	v_ashrrev_i32_e32 v143, 31, v142
	v_ashrrev_i32_e32 v145, 31, v144
	v_lshlrev_b64 v[146:147], 11, v[142:143]
	v_lshl_add_u64 v[146:147], s[2:3], 0, v[146:147]
	v_lshlrev_b64 v[144:145], 2, v[144:145]
	v_lshl_add_u64 v[146:147], v[146:147], 0, v[144:145]
	global_store_dwordx4 v[146:147], v[124:127], off nt
	global_store_dwordx4 v[146:147], v[120:123], off offset:16 nt
	global_store_dwordx4 v[146:147], v[108:111], off offset:512 nt
	global_store_dwordx4 v[146:147], v[100:103], off offset:528 nt
	s_mov_b64 s[4:5], 0x40000
	s_nop 0
	v_or_b32_e32 v100, 16, v142
	v_ashrrev_i32_e32 v101, 31, v100
	v_lshlrev_b64 v[100:101], 11, v[100:101]
	v_lshl_add_u64 v[100:101], s[2:3], 0, v[100:101]
	v_lshl_add_u64 v[100:101], v[100:101], 0, v[144:145]
	global_store_dwordx4 v[100:101], v[116:119], off nt
	global_store_dwordx4 v[100:101], v[112:115], off offset:16 nt
	global_store_dwordx4 v[100:101], v[92:95], off offset:512 nt
	global_store_dwordx4 v[100:101], v[84:87], off offset:528 nt
	s_nop 1
	v_or_b32_e32 v84, 32, v142
	v_ashrrev_i32_e32 v85, 31, v84
	v_lshlrev_b64 v[84:85], 11, v[84:85]
	v_lshl_add_u64 v[84:85], s[2:3], 0, v[84:85]
	v_lshl_add_u64 v[84:85], v[84:85], 0, v[144:145]
	global_store_dwordx4 v[84:85], v[104:107], off nt
	global_store_dwordx4 v[84:85], v[96:99], off offset:16 nt
	global_store_dwordx4 v[84:85], v[76:79], off offset:512 nt
	global_store_dwordx4 v[84:85], v[72:75], off offset:528 nt
	s_nop 1
	v_or_b32_e32 v72, 48, v142
	v_ashrrev_i32_e32 v73, 31, v72
	v_lshlrev_b64 v[72:73], 11, v[72:73]
	v_lshl_add_u64 v[72:73], s[2:3], 0, v[72:73]
	v_lshl_add_u64 v[72:73], v[72:73], 0, v[144:145]
	global_store_dwordx4 v[72:73], v[88:91], off nt
	global_store_dwordx4 v[72:73], v[80:83], off offset:16 nt
	global_store_dwordx4 v[72:73], v[68:71], off offset:512 nt
	global_store_dwordx4 v[72:73], v[64:67], off offset:528 nt
	s_nop 1
	v_lshl_add_u64 v[64:65], v[146:147], 0, s[4:5]
	s_mov_b32 s4, 0x40000
	v_add_co_u32_e32 v66, vcc, s4, v146
	s_mov_b64 s[4:5], 0x48000
	s_nop 0
	v_addc_co_u32_e32 v67, vcc, 0, v147, vcc
	global_store_dwordx4 v[66:67], v[60:63], off nt
	global_store_dwordx4 v[64:65], v[56:59], off offset:16 nt
	global_store_dwordx4 v[64:65], v[44:47], off offset:512 nt
	global_store_dwordx4 v[64:65], v[40:43], off offset:528 nt
	s_nop 1
	v_lshl_add_u64 v[40:41], v[146:147], 0, s[4:5]
	s_mov_b32 s4, 0x48000
	v_add_co_u32_e32 v42, vcc, s4, v146
	s_mov_b64 s[4:5], 0x50000
	s_nop 0
	v_addc_co_u32_e32 v43, vcc, 0, v147, vcc
	global_store_dwordx4 v[42:43], v[52:55], off nt
	global_store_dwordx4 v[40:41], v[48:51], off offset:16 nt
	global_store_dwordx4 v[40:41], v[28:31], off offset:512 nt
	global_store_dwordx4 v[40:41], v[24:27], off offset:528 nt
	s_nop 1
	v_lshl_add_u64 v[24:25], v[146:147], 0, s[4:5]
	s_mov_b32 s4, 0x50000
	v_add_co_u32_e32 v26, vcc, s4, v146
	s_mov_b64 s[4:5], 0x58000
	s_nop 0
	v_addc_co_u32_e32 v27, vcc, 0, v147, vcc
	global_store_dwordx4 v[26:27], v[36:39], off nt
	global_store_dwordx4 v[24:25], v[32:35], off offset:16 nt
	global_store_dwordx4 v[24:25], v[12:15], off offset:512 nt
	global_store_dwordx4 v[24:25], v[8:11], off offset:528 nt
	s_nop 1
	v_add_co_u32_e32 v10, vcc, 0x58000, v146
	v_lshl_add_u64 v[8:9], v[146:147], 0, s[4:5]
	s_nop 0
	v_addc_co_u32_e32 v11, vcc, 0, v147, vcc
	s_andn2_b64 vcc, exec, s[8:9]
	s_mov_b64 s[4:5], -1
	global_store_dwordx4 v[10:11], v[20:23], off nt
	global_store_dwordx4 v[8:9], v[16:19], off offset:16 nt
	global_store_dwordx4 v[8:9], v[4:7], off offset:512 nt
	global_store_dwordx4 v[8:9], v[0:3], off offset:528 nt
	s_cbranch_vccnz .LBB0_687
	s_andn2_b64 vcc, exec, s[0:1]
	s_cbranch_vccnz .LBB0_686
	s_barrier
	s_branch .LBB0_686
